# QKV/BIN/BGRP instance: second epilogue half deferred into the next tile's first MFMA block when the row panel is unchanged
# speedup vs baseline: 1.0204x; 1.0056x over previous
;     __device__ bool next(int i, Unit& u) const {
;         const long L = (long)i * G + c; if (L >= nwg) return false;
;         int wgid = (int)L; { const int q = nwg / NXCD, r = nwg % NXCD, xcd = wgid % NXCD, off = wgid / NXCD; wgid = (xcd < r ? xcd * (q + 1) : r * (q + 1) + (xcd - r) * q) + off; }
;         const int nig = WGM * nN, gid = wgid / nig, fm = gid * WGM, gsz = (nM - fm) < WGM ? (nM - fm) : WGM;
;         u.pm = fm + ((wgid % nig) % gsz); u.pn = (wgid % nig) / gsz; return true;
;     }
; template <class Epi, bool ALIGN_EPI>
; __device__ __forceinline__ void gemm_phase(LAS unsigned char* lds, const Gemm g, const StaticOrder& S, const Epi& E, const int tid) {
;     ...
;         const bool has_next = S.next(ui + 1, nxt);
;         const char* nA = has_next ? (const char*)g.A + (size_t)nxt.pm * tA + (size_t)nxt.pn * g.apn * 2 : cA; const char* nB = has_next ? (const char*)g.Bt + (size_t)nxt.pn * tB : cB;
.LBB0_346:
	s_add_i32 s57, s57, 1
	s_mul_i32 s8, s57, s56
	s_mul_hi_u32 s9, s57, s6
	s_add_i32 s9, s9, s8
	s_mul_i32 s8, s57, s6
	s_add_u32 s8, s8, s0
	s_addc_u32 s9, s9, s47
	v_mov_b64_e32 v[224:225], s[38:39]
	v_cmp_ge_i64_e32 vcc, s[8:9], v[224:225]
	v_cmp_lt_i64_e64 s[10:11], s[8:9], v[224:225]
	s_cbranch_vccnz .LBB0_348
	s_ashr_i32 s9, s8, 31
	s_lshr_b32 s9, s9, 29
	s_add_i32 s9, s8, s9
	s_ashr_i32 s58, s9, 3
	s_and_b32 s9, s9, -8
	s_sub_i32 s8, s8, s9
	s_cmp_lt_i32 s8, 0
	s_cselect_b32 s9, s48, s46
	s_mul_i32 s8, s9, s8
	s_add_i32 s8, s8, s58
	s_abs_i32 s58, s8
	s_mul_hi_u32 s59, s58, s49
	s_mul_i32 s62, s59, s7
	s_sub_i32 s58, s58, s62
	s_ashr_i32 s9, s8, 31
	s_add_i32 s62, s59, 1
	s_sub_i32 s63, s58, s7
	s_cmp_ge_u32 s58, s7
	s_cselect_b32 s59, s62, s59
	s_cselect_b32 s58, s63, s58
	s_add_i32 s62, s59, 1
	s_cmp_ge_u32 s58, s7
	s_cselect_b32 s58, s62, s59
	s_xor_b32 s58, s58, s9
	s_sub_i32 s9, s58, s9
	s_lshl_b32 s59, s9, 3
	s_sub_i32 s58, 0x80, s59
	s_min_i32 s62, s58, 8
	s_abs_i32 s58, s62
	v_cvt_f32_u32_e32 v224, s58
	s_sub_i32 s64, 0, s58
	s_mul_i32 s9, s9, s7
	s_sub_i32 s8, s8, s9
	v_rcp_iflag_f32_e32 v224, v224
	s_abs_i32 s63, s8
	s_xor_b32 s9, s8, s62
	s_ashr_i32 s9, s9, 31
	v_mul_f32_e32 v224, 0x4f7ffffe, v224
	v_cvt_u32_f32_e32 v224, v224
	s_nop 0
	v_readfirstlane_b32 s65, v224
	s_mul_i32 s64, s64, s65
	s_mul_hi_u32 s64, s65, s64
	s_add_i32 s65, s65, s64
	s_mul_hi_u32 s64, s63, s65
	s_mul_i32 s65, s64, s58
	s_sub_i32 s63, s63, s65
	s_add_i32 s65, s64, 1
	s_sub_i32 s66, s63, s58
	s_cmp_ge_u32 s63, s58
	s_cselect_b32 s64, s65, s64
	s_cselect_b32 s63, s66, s63
	s_add_i32 s65, s64, 1
	s_cmp_ge_u32 s63, s58
	s_cselect_b32 s58, s65, s64
	s_xor_b32 s58, s58, s9
	s_sub_i32 s58, s58, s9
	s_mul_i32 s9, s58, s62
	s_sub_i32 s8, s8, s9
	s_add_i32 s59, s8, s59
.LBB0_348:
	s_nop 0
	v_cndmask_b32_e64 v224, 0, 1, s[10:11]
	v_cmp_ne_u32_e64 s[8:9], 1, v224
	s_andn2_b64 vcc, exec, s[10:11]
	v_mov_b64_e32 v[138:139], v[142:143]
	s_cbranch_vccnz .LBB0_350
	s_ashr_i32 s10, s59, 31
	s_mul_hi_u32 s11, s14, s59
	s_mul_i32 s10, s14, s10
	s_add_i32 s10, s11, s10
	s_mul_i32 s11, s15, s59
	s_add_i32 s11, s10, s11
	s_mul_i32 s10, s14, s59
	v_lshl_add_u64 v[224:225], v[174:175], 0, s[10:11]
	s_ashr_i32 s10, s58, 31
	s_mul_hi_u32 s11, s16, s58
	s_mul_i32 s10, s16, s10
	s_add_i32 s10, s11, s10
	s_mul_i32 s11, s17, s58
	s_add_i32 s11, s10, s11
	s_mul_i32 s10, s16, s58
	v_lshl_add_u64 v[138:139], v[224:225], 0, s[10:11]

; #define PG8_STAGE(bufoff, gbase, voff) do { _Pragma("unroll") for (int _i = 0; _i < 2; ++_i) \
;         __builtin_amdgcn_global_load_lds((const unsigned*)((const char*)(gbase) + (voff)[_i]), (LAS unsigned*)(lds + (bufoff) + ldsw + _i * 8192), 16, 0, 0); } while (0)
; #define PG8_LDA(dst, b, h) do { _Pragma("unroll") for (int m = 0; m < 4; ++m) _Pragma("unroll") for (int k = 0; k < 2; ++k) dst[m][k] = *(const LAS bf16x8*)(lds + PG8_SA(b, h) + aoff + m * 2048 + k * 1024); } while (0)
; #define PG8_LDB(dst, b, h) do { _Pragma("unroll") for (int n = 0; n < 2; ++n) _Pragma("unroll") for (int k = 0; k < 2; ++k) dst[n][k] = *(const LAS bf16x8*)(lds + PG8_SB(b, h) + boff + n * 2048 + k * 1024); } while (0)
; #define PG8_SCHED __builtin_amdgcn_sched_barrier(0)
; __device__ __forceinline__ void load_rstd(float (&rsv)[2][4], const ssq_t* ssq, int row0) {
;     ssq_t t[2][4];
; #pragma unroll
;     for (int ai = 0; ai < 2; ++ai)
; #pragma unroll
;         for (int m = 0; m < 4; ++m) t[ai][m] = ssq[row0 + ai * HALF + m * 16];
; #pragma unroll
;     for (int ai = 0; ai < 2; ++ai)
; #pragma unroll
;         for (int m = 0; m < 4; ++m) rsv[ai][m] = __builtin_amdgcn_rsqf((float)t[ai][m] * (SSQ_INV / 1024.0f) + 1e-6f);
; }
; template <class Epi, bool ALIGN_EPI>
; __device__ __forceinline__ void gemm_phase(LAS unsigned char* lds, const Gemm g, const StaticOrder& S, const Epi& E, const int tid) {
;     ...
;             PG8_LDB(B0, 0, 0); PG8_LDB(B1, 0, 1); PG8_SCHED; PG8_LDA(At, 0, 0); PG8_STAGE(PG8_SA(1, 1), a1 + hA, voffA);
.LBB0_352:
	s_andn2_b64 vcc, exec, s[36:37]
	s_cbranch_vccnz .LBB0_355
	v_lshl_add_u64 v[142:143], v[142:143], 0, s[92:93]
	v_lshl_add_u64 v[144:145], v[144:145], 0, s[80:81]
	s_mov_b32 s10, 0
	v_readfirstlane_b32 s98, v254
	s_cmp_eq_u32 s98, s61
	s_cbranch_scc1 .Lq5_rs_ok
	v_lshrrev_b32_e32 v194, 8, v170
	v_and_b32_e32 v195, 15, v170
	v_lshl_add_u32 v194, v194, 6, v195
	s_lshl_b32 s98, s61, 8
	v_add_u32_e32 v194, s98, v194
	v_lshlrev_b32_e32 v192, 3, v194
	v_mov_b32_e32 v193, 0
	v_lshl_add_u64 v[192:193], v[192:193], 0, s[26:27]
	global_load_dwordx2 v[176:177], v[192:193], off
	global_load_dwordx2 v[178:179], v[192:193], off offset:128
	global_load_dwordx2 v[180:181], v[192:193], off offset:256
	global_load_dwordx2 v[182:183], v[192:193], off offset:384
	global_load_dwordx2 v[184:185], v[192:193], off offset:1024
	global_load_dwordx2 v[186:187], v[192:193], off offset:1152
	global_load_dwordx2 v[188:189], v[192:193], off offset:1280
	global_load_dwordx2 v[190:191], v[192:193], off offset:1408
	s_waitcnt vmcnt(0)
	v_ffbh_u32_e32 v194, v177
	v_min_u32_e32 v194, 32, v194
	v_lshlrev_b64 v[176:177], v194, v[176:177]
	v_min_u32_e32 v176, 1, v176
	v_or_b32_e32 v176, v177, v176
	v_cvt_f32_u32_e32 v176, v176
	v_sub_u32_e32 v194, 32, v194
	v_ldexp_f32 v176, v176, v194
	v_fmamk_f32 v176, v176, 0x30800000, v223
	v_rsq_f32_e32 v176, v176
	v_ffbh_u32_e32 v194, v179
	v_min_u32_e32 v194, 32, v194
	v_lshlrev_b64 v[178:179], v194, v[178:179]
	v_min_u32_e32 v178, 1, v178
	v_or_b32_e32 v178, v179, v178
	v_cvt_f32_u32_e32 v178, v178
	v_sub_u32_e32 v194, 32, v194
	v_ldexp_f32 v178, v178, v194
	v_fmamk_f32 v178, v178, 0x30800000, v223
	v_rsq_f32_e32 v178, v178
	v_ffbh_u32_e32 v194, v181
	v_min_u32_e32 v194, 32, v194
	v_lshlrev_b64 v[180:181], v194, v[180:181]
	v_min_u32_e32 v180, 1, v180
	v_or_b32_e32 v180, v181, v180
	v_cvt_f32_u32_e32 v180, v180
	v_sub_u32_e32 v194, 32, v194
	v_ldexp_f32 v180, v180, v194
	v_fmamk_f32 v180, v180, 0x30800000, v223
	v_rsq_f32_e32 v180, v180
	v_ffbh_u32_e32 v194, v183
	v_min_u32_e32 v194, 32, v194
	v_lshlrev_b64 v[182:183], v194, v[182:183]
	v_min_u32_e32 v182, 1, v182
	v_or_b32_e32 v182, v183, v182
	v_cvt_f32_u32_e32 v182, v182
	v_sub_u32_e32 v194, 32, v194
	v_ldexp_f32 v182, v182, v194
	v_fmamk_f32 v182, v182, 0x30800000, v223
	v_rsq_f32_e32 v182, v182
	v_ffbh_u32_e32 v194, v185
	v_min_u32_e32 v194, 32, v194
	v_lshlrev_b64 v[184:185], v194, v[184:185]
	v_min_u32_e32 v184, 1, v184
	v_or_b32_e32 v184, v185, v184
	v_cvt_f32_u32_e32 v184, v184
	v_sub_u32_e32 v194, 32, v194
	v_ldexp_f32 v184, v184, v194
	v_fmamk_f32 v184, v184, 0x30800000, v223
	v_rsq_f32_e32 v184, v184
	v_ffbh_u32_e32 v194, v187
	v_min_u32_e32 v194, 32, v194
	v_lshlrev_b64 v[186:187], v194, v[186:187]
	v_min_u32_e32 v186, 1, v186
	v_or_b32_e32 v186, v187, v186
	v_cvt_f32_u32_e32 v186, v186
	v_sub_u32_e32 v194, 32, v194
	v_ldexp_f32 v186, v186, v194
	v_fmamk_f32 v186, v186, 0x30800000, v223
	v_rsq_f32_e32 v186, v186
	v_ffbh_u32_e32 v194, v189
	v_min_u32_e32 v194, 32, v194
	v_lshlrev_b64 v[188:189], v194, v[188:189]
	v_min_u32_e32 v188, 1, v188
	v_or_b32_e32 v188, v189, v188
	v_cvt_f32_u32_e32 v188, v188
	v_sub_u32_e32 v194, 32, v194
	v_ldexp_f32 v188, v188, v194
	v_fmamk_f32 v188, v188, 0x30800000, v223
	v_rsq_f32_e32 v188, v188
	v_ffbh_u32_e32 v194, v191
	v_min_u32_e32 v194, 32, v194
	v_lshlrev_b64 v[190:191], v194, v[190:191]
	v_min_u32_e32 v190, 1, v190
	v_or_b32_e32 v190, v191, v190
	v_cvt_f32_u32_e32 v190, v190
	v_sub_u32_e32 v194, 32, v194
	v_ldexp_f32 v190, v190, v194
	v_fmamk_f32 v190, v190, 0x30800000, v223
	v_rsq_f32_e32 v190, v190
	v_mov_b32_e32 v172, v176
	v_mov_b32_e32 v173, v178
	v_mov_b32_e32 v236, v180
	v_mov_b32_e32 v237, v182
	v_mov_b32_e32 v238, v184
	v_mov_b32_e32 v239, v186
	v_mov_b32_e32 v230, v188
	v_mov_b32_e32 v231, v190
	v_mov_b32_e32 v254, s61
.Lq5_rs_ok:
	s_cmp_eq_u32 s101, 0
	s_cbranch_scc1 .Lq5_first
.Lq5_first_epi:
	s_add_i32 s11, s10, 2
	s_cmp_eq_u32 s55, s10
	s_cselect_b64 vcc, -1, 0
	v_add_u32_e32 v148, s33, v149
	s_add_i32 s10, 0, 0x14000
	ds_read_b128 v[152:155], v148
	ds_read_b128 v[156:159], v148 offset:1024
	ds_read_b128 v[160:163], v148 offset:2048
	ds_read_b128 v[164:167], v148 offset:3072
	v_add_u32_e32 v148, s10, v149
	ds_read_b128 v[176:179], v148
	ds_read_b128 v[180:183], v148 offset:1024
	ds_read_b128 v[184:187], v148 offset:2048
	ds_read_b128 v[188:191], v148 offset:3072
	v_lshl_add_u64 v[146:147], v[142:143], 0, s[92:93]
	v_cndmask_b32_e32 v147, v147, v139, vcc
	v_cndmask_b32_e32 v146, v146, v138, vcc
	v_cndmask_b32_e32 v221, v145, v141, vcc
	v_cndmask_b32_e32 v220, v144, v140, vcc
	v_lshl_add_u64 v[244:245], v[142:143], 0, v[134:135]
	s_add_i32 m0, s25, 0xc000
	ds_read_b128 v[192:195], v151
	ds_read_b128 v[196:199], v151 offset:1024
	ds_read_b128 v[200:203], v151 offset:2048
	ds_read_b128 v[204:207], v151 offset:3072
	ds_read_b128 v[208:211], v151 offset:4096
	ds_read_b128 v[212:215], v151 offset:5120
	ds_read_b128 v[216:219], v151 offset:6144
	ds_read_b128 v[240:243], v151 offset:7168
	global_load_lds_dwordx4 v[244:245], off
	v_lshl_add_u64 v[244:245], v[142:143], 0, v[136:137]
	s_add_i32 m0, s25, 0xe000
	s_nop 0
	global_load_lds_dwordx4 v[244:245], off
	s_waitcnt vmcnt(8)
	s_waitcnt lgkmcnt(0)
	s_barrier
; __device__ __forceinline__ unsigned cvt_pk_bf16(float lo, float hi) { unsigned r; asm volatile("v_cvt_pk_bf16_f32 %0, %1, %2" : "=v"(r) : "v"(lo), "v"(hi)); return r; }
; __device__ __forceinline__ float gelu_tanh(float x) { const float u = 0.7978845608028654f * (x + 0.044715f * x * x * x); return x * fast_rcp(1.0f + fast_exp2(-2.0f * LOG2E * u)); }
; #define PG8_MMA(ai, bj, At, Bt) do { __builtin_amdgcn_s_setprio(1); _Pragma("unroll") for (int k = 0; k < 2; ++k) _Pragma("unroll") for (int m = 0; m < 4; ++m) _Pragma("unroll") for (int n = 0; n < 2; ++n) \
;         acc[ai][bj][m][n] = __builtin_amdgcn_mfma_f32_16x16x32_bf16(Bt[n][k], At[m][k], acc[ai][bj][m][n], 0, 0, 0); __builtin_amdgcn_s_setprio(0); } while (0)
; #define PG8_WAIT_V(n) asm volatile("s_waitcnt vmcnt(" #n ")" ::: "memory")
; #define PG8_WAIT_L(n) asm volatile("s_waitcnt lgkmcnt(" #n ")" ::: "memory")
; #define PG8_BAR __builtin_amdgcn_s_barrier()
; #define PG8_SCHED __builtin_amdgcn_sched_barrier(0)
;     __device__ __forceinline__ void operator()(const f32x4 (&acc)[2][2][4][2], const Unit& u, int wr, int wc, int fr, int fq) const {
;     ...
;             for (int m = 0; m < 4; ++m) { const int row = row0 + ai * HALF + m * 16; bf16_t* rowp = O + (size_t)row * ldc + col0; const float rs = rsv[ai][m];
; #pragma unroll
;                 for (int bj = 0; bj < 2; ++bj) { f32x4 v0 = acc[ai][bj][m][0] * rs, v1 = acc[ai][bj][m][1] * rs;
;                     if (ACT == 1) {
; #pragma unroll
;                         for (int j = 0; j < 4; ++j) { v0[j] = gelu_tanh(v0[j]); v1[j] = gelu_tanh(v1[j]); } }
;                     u32x4 w; w.x = cvt_pk_bf16(v0[0], v0[1]); w.y = cvt_pk_bf16(v0[2], v0[3]); w.z = cvt_pk_bf16(v1[0], v1[1]); w.w = cvt_pk_bf16(v1[2], v1[3]);
;                     *(u32x4*)(rowp + bj * HALF) = w; } }
; template <class Epi, bool ALIGN_EPI>
; __device__ __forceinline__ void gemm_phase(LAS unsigned char* lds, const Gemm g, const StaticOrder& S, const Epi& E, const int tid) {
;     ...
;             PG8_WAIT_V(8); PG8_WAIT_L(0); PG8_BAR; PG8_MMA(0, 0, At, B0); PG8_MMA(0, 1, At, B1); PG8_BAR; PG8_SCHED;
	s_setprio 1
	s_waitcnt lgkmcnt(0)
	v_mfma_f32_16x16x32_bf16 v[124:127], v[152:155], v[192:195], 0
	s_lshl_b32 s98, s28, 5
	s_mov_b32 s99, 0
	v_mul_f32_e32 v60, v238, v60
	v_mul_f32_e32 v61, v238, v61
	v_mfma_f32_16x16x32_bf16 v[120:123], v[160:163], v[192:195], 0
	v_mul_f32_e32 v62, v238, v62
	v_mul_f32_e32 v63, v238, v63
	v_mul_f32_e32 v56, v238, v56
	v_mul_f32_e32 v57, v238, v57
	v_mfma_f32_16x16x32_bf16 v[108:111], v[152:155], v[200:203], 0
	v_mul_f32_e32 v58, v238, v58
	v_mul_f32_e32 v59, v238, v59
	v_cvt_pk_bf16_f32 v60, v60, v61
	v_cvt_pk_bf16_f32 v61, v62, v63
	v_mfma_f32_16x16x32_bf16 v[104:107], v[160:163], v[200:203], 0
	v_cvt_pk_bf16_f32 v62, v56, v57
	v_cvt_pk_bf16_f32 v63, v58, v59
	global_store_dwordx4 v[232:233], v[60:63], off
	v_mul_f32_e32 v52, v238, v52
	v_mfma_f32_16x16x32_bf16 v[92:95], v[152:155], v[208:211], 0
	v_mul_f32_e32 v53, v238, v53
	v_mul_f32_e32 v54, v238, v54
	v_mul_f32_e32 v55, v238, v55
	v_mul_f32_e32 v48, v238, v48
	v_mfma_f32_16x16x32_bf16 v[88:91], v[160:163], v[208:211], 0
	v_mul_f32_e32 v49, v238, v49
	v_mul_f32_e32 v50, v238, v50
	v_mul_f32_e32 v51, v238, v51
	v_cvt_pk_bf16_f32 v52, v52, v53
	v_mfma_f32_16x16x32_bf16 v[76:79], v[152:155], v[216:219], 0
	v_cvt_pk_bf16_f32 v53, v54, v55
	v_cvt_pk_bf16_f32 v54, v48, v49
	v_cvt_pk_bf16_f32 v55, v50, v51
	global_store_dwordx4 v[232:233], v[52:55], off offset:256
	v_mfma_f32_16x16x32_bf16 v[72:75], v[160:163], v[216:219], 0
	v_lshl_add_u64 v[232:233], v[232:233], 0, s[98:99]
	v_mul_f32_e32 v44, v239, v44
	v_mul_f32_e32 v45, v239, v45
	v_mul_f32_e32 v46, v239, v46
	v_mfma_f32_16x16x32_bf16 v[124:127], v[156:159], v[196:199], v[124:127]
	v_mul_f32_e32 v47, v239, v47
	v_mul_f32_e32 v40, v239, v40
	v_mul_f32_e32 v41, v239, v41
	v_mul_f32_e32 v42, v239, v42
	v_mfma_f32_16x16x32_bf16 v[120:123], v[164:167], v[196:199], v[120:123]
	v_mul_f32_e32 v43, v239, v43
	v_cvt_pk_bf16_f32 v44, v44, v45
	v_cvt_pk_bf16_f32 v45, v46, v47
	v_cvt_pk_bf16_f32 v46, v40, v41
	v_mfma_f32_16x16x32_bf16 v[108:111], v[156:159], v[204:207], v[108:111]
	v_cvt_pk_bf16_f32 v47, v42, v43
	global_store_dwordx4 v[232:233], v[44:47], off
	v_mul_f32_e32 v36, v239, v36
	v_mul_f32_e32 v37, v239, v37
	v_mfma_f32_16x16x32_bf16 v[104:107], v[164:167], v[204:207], v[104:107]
	v_mul_f32_e32 v38, v239, v38
	v_mul_f32_e32 v39, v239, v39
	v_mul_f32_e32 v32, v239, v32
	v_mul_f32_e32 v33, v239, v33
	v_mfma_f32_16x16x32_bf16 v[92:95], v[156:159], v[212:215], v[92:95]
	v_mul_f32_e32 v34, v239, v34
	v_mul_f32_e32 v35, v239, v35
	v_cvt_pk_bf16_f32 v36, v36, v37
	v_cvt_pk_bf16_f32 v37, v38, v39
	v_mfma_f32_16x16x32_bf16 v[88:91], v[164:167], v[212:215], v[88:91]
	v_cvt_pk_bf16_f32 v38, v32, v33
	v_cvt_pk_bf16_f32 v39, v34, v35
	global_store_dwordx4 v[232:233], v[36:39], off offset:256
	v_lshl_add_u64 v[232:233], v[232:233], 0, s[98:99]
	v_mfma_f32_16x16x32_bf16 v[76:79], v[156:159], v[240:243], v[76:79]
	v_mul_f32_e32 v28, v230, v28
	v_mul_f32_e32 v29, v230, v29
	v_mul_f32_e32 v30, v230, v30
	v_mul_f32_e32 v31, v230, v31
	v_mfma_f32_16x16x32_bf16 v[72:75], v[164:167], v[240:243], v[72:75]
	v_mul_f32_e32 v24, v230, v24
	v_mul_f32_e32 v25, v230, v25
	v_mul_f32_e32 v26, v230, v26
	v_mul_f32_e32 v27, v230, v27
	s_setprio 0
	s_setprio 1
	v_mfma_f32_16x16x32_bf16 v[116:119], v[176:179], v[192:195], 0
	v_cvt_pk_bf16_f32 v28, v28, v29
	v_cvt_pk_bf16_f32 v29, v30, v31
	v_cvt_pk_bf16_f32 v30, v24, v25
	v_cvt_pk_bf16_f32 v31, v26, v27
	v_mfma_f32_16x16x32_bf16 v[112:115], v[184:187], v[192:195], 0
	global_store_dwordx4 v[232:233], v[28:31], off
	v_mul_f32_e32 v20, v230, v20
	v_mul_f32_e32 v21, v230, v21
	v_mul_f32_e32 v22, v230, v22
	v_mfma_f32_16x16x32_bf16 v[100:103], v[176:179], v[200:203], 0
	v_mul_f32_e32 v23, v230, v23
	v_mul_f32_e32 v16, v230, v16
	v_mul_f32_e32 v17, v230, v17
	v_mul_f32_e32 v18, v230, v18
	v_mfma_f32_16x16x32_bf16 v[96:99], v[184:187], v[200:203], 0
	v_mul_f32_e32 v19, v230, v19
	v_cvt_pk_bf16_f32 v20, v20, v21
	v_cvt_pk_bf16_f32 v21, v22, v23
	v_cvt_pk_bf16_f32 v22, v16, v17
	v_mfma_f32_16x16x32_bf16 v[84:87], v[176:179], v[208:211], 0
	v_cvt_pk_bf16_f32 v23, v18, v19
	global_store_dwordx4 v[232:233], v[20:23], off offset:256
	v_lshl_add_u64 v[232:233], v[232:233], 0, s[98:99]
	v_mul_f32_e32 v12, v231, v12
	v_mfma_f32_16x16x32_bf16 v[80:83], v[184:187], v[208:211], 0
	v_mul_f32_e32 v13, v231, v13
	v_mul_f32_e32 v14, v231, v14
	v_mul_f32_e32 v15, v231, v15
	v_mul_f32_e32 v8, v231, v8
	v_mfma_f32_16x16x32_bf16 v[68:71], v[176:179], v[216:219], 0
	v_mul_f32_e32 v9, v231, v9
	v_mul_f32_e32 v10, v231, v10
	v_mul_f32_e32 v11, v231, v11
	v_cvt_pk_bf16_f32 v12, v12, v13
	v_mfma_f32_16x16x32_bf16 v[64:67], v[184:187], v[216:219], 0
	v_cvt_pk_bf16_f32 v13, v14, v15
	v_cvt_pk_bf16_f32 v14, v8, v9
	v_cvt_pk_bf16_f32 v15, v10, v11
	global_store_dwordx4 v[232:233], v[12:15], off
	v_mfma_f32_16x16x32_bf16 v[116:119], v[180:183], v[196:199], v[116:119]
	v_mul_f32_e32 v4, v231, v4
	v_mul_f32_e32 v5, v231, v5
	v_mul_f32_e32 v6, v231, v6
	v_mul_f32_e32 v7, v231, v7
	v_mfma_f32_16x16x32_bf16 v[112:115], v[188:191], v[196:199], v[112:115]
	v_mul_f32_e32 v0, v231, v0
	v_mul_f32_e32 v1, v231, v1
	v_mul_f32_e32 v2, v231, v2
	v_mul_f32_e32 v3, v231, v3
	v_mfma_f32_16x16x32_bf16 v[100:103], v[180:183], v[204:207], v[100:103]
	v_cvt_pk_bf16_f32 v4, v4, v5
	v_cvt_pk_bf16_f32 v5, v6, v7
	v_cvt_pk_bf16_f32 v6, v0, v1
	v_cvt_pk_bf16_f32 v7, v2, v3
	v_mfma_f32_16x16x32_bf16 v[96:99], v[188:191], v[204:207], v[96:99]
	global_store_dwordx4 v[232:233], v[4:7], off offset:256
	v_mfma_f32_16x16x32_bf16 v[84:87], v[180:183], v[212:215], v[84:87]
	v_mfma_f32_16x16x32_bf16 v[80:83], v[188:191], v[212:215], v[80:83]
	v_mfma_f32_16x16x32_bf16 v[68:71], v[180:183], v[240:243], v[68:71]
	v_mfma_f32_16x16x32_bf16 v[64:67], v[188:191], v[240:243], v[64:67]
	s_setprio 0
	s_barrier
; #define PG8_STAGE(bufoff, gbase, voff) do { _Pragma("unroll") for (int _i = 0; _i < 2; ++_i) \
;         __builtin_amdgcn_global_load_lds((const unsigned*)((const char*)(gbase) + (voff)[_i]), (LAS unsigned*)(lds + (bufoff) + ldsw + _i * 8192), 16, 0, 0); } while (0)
; #define PG8_LDA(dst, b, h) do { _Pragma("unroll") for (int m = 0; m < 4; ++m) _Pragma("unroll") for (int k = 0; k < 2; ++k) dst[m][k] = *(const LAS bf16x8*)(lds + PG8_SA(b, h) + aoff + m * 2048 + k * 1024); } while (0)
; #define PG8_LDB(dst, b, h) do { _Pragma("unroll") for (int n = 0; n < 2; ++n) _Pragma("unroll") for (int k = 0; k < 2; ++k) dst[n][k] = *(const LAS bf16x8*)(lds + PG8_SB(b, h) + boff + n * 2048 + k * 1024); } while (0)
; #define PG8_MMA(ai, bj, At, Bt) do { __builtin_amdgcn_s_setprio(1); _Pragma("unroll") for (int k = 0; k < 2; ++k) _Pragma("unroll") for (int m = 0; m < 4; ++m) _Pragma("unroll") for (int n = 0; n < 2; ++n) \
;         acc[ai][bj][m][n] = __builtin_amdgcn_mfma_f32_16x16x32_bf16(Bt[n][k], At[m][k], acc[ai][bj][m][n], 0, 0, 0); __builtin_amdgcn_s_setprio(0); } while (0)
; #define PG8_WAIT_V(n) asm volatile("s_waitcnt vmcnt(" #n ")" ::: "memory")
; #define PG8_WAIT_L(n) asm volatile("s_waitcnt lgkmcnt(" #n ")" ::: "memory")
; #define PG8_BAR __builtin_amdgcn_s_barrier()
; #define PG8_SCHED __builtin_amdgcn_sched_barrier(0)
; template <class Epi, bool ALIGN_EPI>
; __device__ __forceinline__ void gemm_phase(LAS unsigned char* lds, const Gemm g, const StaticOrder& S, const Epi& E, const int tid) {
;     ...
;             PG8_LDA(At, 0, 1); PG8_STAGE(PG8_SB(0, 0), b2, voffB); PG8_STAGE(PG8_SB(0, 1), b2 + hB, voffB); PG8_STAGE(PG8_SA(0, 0), a2, voffA);
;             PG8_WAIT_V(8); PG8_WAIT_L(0); PG8_BAR; PG8_MMA(1, 0, At, B0); PG8_MMA(1, 1, At, B1); PG8_BAR; PG8_SCHED;
;             PG8_LDB(B0, 1, 0); PG8_LDB(B1, 1, 1); PG8_SCHED; PG8_LDA(At, 1, 0); PG8_STAGE(PG8_SA(0, 1), a2 + hA, voffA);
;             PG8_WAIT_V(8); PG8_WAIT_L(0); PG8_BAR; PG8_MMA(0, 0, At, B0); PG8_MMA(0, 1, At, B1); PG8_BAR; PG8_SCHED;
;             PG8_LDA(At, 1, 1); PG8_STAGE(PG8_SB(1, 0), b3, voffB); PG8_STAGE(PG8_SB(1, 1), b3 + hB, voffB); PG8_STAGE(PG8_SA(1, 0), a3, voffA);
	s_add_i32 s62, s33, s45
	v_lshl_add_u64 v[244:245], v[220:221], 0, v[168:169]
	s_mov_b32 m0, s62
	ds_read_b128 v[192:195], v151 offset:16384
	ds_read_b128 v[196:199], v151 offset:17408
	ds_read_b128 v[200:203], v151 offset:18432
	ds_read_b128 v[204:207], v151 offset:19456
	ds_read_b128 v[208:211], v151 offset:20480
	ds_read_b128 v[212:215], v151 offset:21504
	ds_read_b128 v[216:219], v151 offset:22528
	ds_read_b128 v[240:243], v151 offset:23552
	global_load_lds_dwordx4 v[244:245], off
	v_lshl_add_u64 v[246:247], v[220:221], 0, v[128:129]
	s_add_i32 m0, s62, 0x2000
	v_lshl_add_u64 v[220:221], v[220:221], 0, s[12:13]
	s_add_i32 s10, s10, s45
	global_load_lds_dwordx4 v[246:247], off
	v_lshl_add_u64 v[248:249], v[220:221], 0, v[168:169]
	s_mov_b32 m0, s10
	v_lshl_add_u64 v[220:221], v[220:221], 0, v[128:129]
	global_load_lds_dwordx4 v[248:249], off
	s_add_i32 m0, s10, 0x2000
	v_lshl_add_u64 v[250:251], v[146:147], 0, v[132:133]
	global_load_lds_dwordx4 v[220:221], off
	s_mov_b32 m0, s25
	v_lshl_add_u64 v[252:253], v[146:147], 0, v[130:131]
	global_load_lds_dwordx4 v[250:251], off
	s_mov_b32 m0, s50
	s_nop 0
	global_load_lds_dwordx4 v[252:253], off
	s_waitcnt vmcnt(8)
	s_waitcnt lgkmcnt(0)
	s_barrier
	s_setprio 1
	s_waitcnt lgkmcnt(0)
	v_mfma_f32_16x16x32_bf16 v[60:63], v[152:155], v[192:195], 0
	v_mfma_f32_16x16x32_bf16 v[56:59], v[160:163], v[192:195], 0
	v_mfma_f32_16x16x32_bf16 v[44:47], v[152:155], v[200:203], 0
	v_mfma_f32_16x16x32_bf16 v[40:43], v[160:163], v[200:203], 0
	v_mfma_f32_16x16x32_bf16 v[28:31], v[152:155], v[208:211], 0
	v_mfma_f32_16x16x32_bf16 v[24:27], v[160:163], v[208:211], 0
	v_mfma_f32_16x16x32_bf16 v[12:15], v[152:155], v[216:219], 0
	v_mfma_f32_16x16x32_bf16 v[8:11], v[160:163], v[216:219], 0
	v_mfma_f32_16x16x32_bf16 v[60:63], v[156:159], v[196:199], v[60:63]
	v_mfma_f32_16x16x32_bf16 v[56:59], v[164:167], v[196:199], v[56:59]
	v_mfma_f32_16x16x32_bf16 v[44:47], v[156:159], v[204:207], v[44:47]
	v_mfma_f32_16x16x32_bf16 v[40:43], v[164:167], v[204:207], v[40:43]
	v_mfma_f32_16x16x32_bf16 v[28:31], v[156:159], v[212:215], v[28:31]
	v_mfma_f32_16x16x32_bf16 v[24:27], v[164:167], v[212:215], v[24:27]
	v_mfma_f32_16x16x32_bf16 v[12:15], v[156:159], v[240:243], v[12:15]
	v_mfma_f32_16x16x32_bf16 v[8:11], v[164:167], v[240:243], v[8:11]
	s_setprio 0
	s_setprio 1
	v_mfma_f32_16x16x32_bf16 v[52:55], v[176:179], v[192:195], 0
	v_mfma_f32_16x16x32_bf16 v[48:51], v[184:187], v[192:195], 0
	v_mfma_f32_16x16x32_bf16 v[36:39], v[176:179], v[200:203], 0
	v_mfma_f32_16x16x32_bf16 v[32:35], v[184:187], v[200:203], 0
	v_mfma_f32_16x16x32_bf16 v[20:23], v[176:179], v[208:211], 0
	v_mfma_f32_16x16x32_bf16 v[16:19], v[184:187], v[208:211], 0
	v_mfma_f32_16x16x32_bf16 v[4:7], v[176:179], v[216:219], 0
	v_mfma_f32_16x16x32_bf16 v[0:3], v[184:187], v[216:219], 0
	v_mfma_f32_16x16x32_bf16 v[52:55], v[180:183], v[196:199], v[52:55]
	v_mfma_f32_16x16x32_bf16 v[48:51], v[188:191], v[196:199], v[48:51]
	v_mfma_f32_16x16x32_bf16 v[36:39], v[180:183], v[204:207], v[36:39]
	v_mfma_f32_16x16x32_bf16 v[32:35], v[188:191], v[204:207], v[32:35]
	v_mfma_f32_16x16x32_bf16 v[20:23], v[180:183], v[212:215], v[20:23]
	v_mfma_f32_16x16x32_bf16 v[16:19], v[188:191], v[212:215], v[16:19]
	v_mfma_f32_16x16x32_bf16 v[4:7], v[180:183], v[240:243], v[4:7]
	v_mfma_f32_16x16x32_bf16 v[0:3], v[188:191], v[240:243], v[0:3]
	s_setprio 0
	s_barrier
	s_add_i32 s10, 0, 0x18000
	v_add_u32_e32 v148, s10, v149
	s_add_i32 s62, 0, 0x1c000
	ds_read_b128 v[152:155], v148
	ds_read_b128 v[156:159], v148 offset:1024
	ds_read_b128 v[160:163], v148 offset:2048
	ds_read_b128 v[164:167], v148 offset:3072
	v_add_u32_e32 v148, s62, v149
	ds_read_b128 v[176:179], v148
	ds_read_b128 v[180:183], v148 offset:1024
	ds_read_b128 v[184:187], v148 offset:2048
	ds_read_b128 v[188:191], v148 offset:3072
	v_lshl_add_u64 v[146:147], v[146:147], 0, s[94:95]
	s_mov_b32 m0, s51
	v_lshl_add_u64 v[226:227], v[146:147], 0, v[132:133]
	ds_read_b128 v[192:195], v151 offset:32768
	ds_read_b128 v[196:199], v151 offset:33792
	ds_read_b128 v[200:203], v151 offset:34816
	ds_read_b128 v[204:207], v151 offset:35840
	ds_read_b128 v[208:211], v151 offset:36864
	ds_read_b128 v[212:215], v151 offset:37888
	ds_read_b128 v[216:219], v151 offset:38912
	ds_read_b128 v[240:243], v151 offset:39936
	global_load_lds_dwordx4 v[226:227], off
	v_lshl_add_u64 v[146:147], v[146:147], 0, v[130:131]
	s_mov_b32 m0, s52
	s_nop 0
	global_load_lds_dwordx4 v[146:147], off
	s_waitcnt vmcnt(8)
	s_waitcnt lgkmcnt(0)
	s_barrier
; #define PG8_STAGE(bufoff, gbase, voff) do { _Pragma("unroll") for (int _i = 0; _i < 2; ++_i) \
;         __builtin_amdgcn_global_load_lds((const unsigned*)((const char*)(gbase) + (voff)[_i]), (LAS unsigned*)(lds + (bufoff) + ldsw + _i * 8192), 16, 0, 0); } while (0)
; #define PG8_LDA(dst, b, h) do { _Pragma("unroll") for (int m = 0; m < 4; ++m) _Pragma("unroll") for (int k = 0; k < 2; ++k) dst[m][k] = *(const LAS bf16x8*)(lds + PG8_SA(b, h) + aoff + m * 2048 + k * 1024); } while (0)
; #define PG8_MMA(ai, bj, At, Bt) do { __builtin_amdgcn_s_setprio(1); _Pragma("unroll") for (int k = 0; k < 2; ++k) _Pragma("unroll") for (int m = 0; m < 4; ++m) _Pragma("unroll") for (int n = 0; n < 2; ++n) \
;         acc[ai][bj][m][n] = __builtin_amdgcn_mfma_f32_16x16x32_bf16(Bt[n][k], At[m][k], acc[ai][bj][m][n], 0, 0, 0); __builtin_amdgcn_s_setprio(0); } while (0)
; #define PG8_WAIT_V(n) asm volatile("s_waitcnt vmcnt(" #n ")" ::: "memory")
; #define PG8_WAIT_L(n) asm volatile("s_waitcnt lgkmcnt(" #n ")" ::: "memory")
; #define PG8_BAR __builtin_amdgcn_s_barrier()
; #define PG8_SCHED __builtin_amdgcn_sched_barrier(0)
; template <class Epi, bool ALIGN_EPI>
; __device__ __forceinline__ void gemm_phase(LAS unsigned char* lds, const Gemm g, const StaticOrder& S, const Epi& E, const int tid) {
;     ...
;             PG8_WAIT_V(8); PG8_WAIT_L(0); PG8_BAR; PG8_MMA(0, 0, At, B0); PG8_MMA(0, 1, At, B1); PG8_BAR; PG8_SCHED;
;             PG8_LDA(At, 1, 1); PG8_STAGE(PG8_SB(1, 0), b3, voffB); PG8_STAGE(PG8_SB(1, 1), b3 + hB, voffB); PG8_STAGE(PG8_SA(1, 0), a3, voffA);
;             PG8_WAIT_V(8); PG8_WAIT_L(0); PG8_BAR; PG8_MMA(1, 0, At, B0); PG8_MMA(1, 1, At, B1); PG8_BAR; PG8_SCHED;
	s_setprio 1
	s_waitcnt lgkmcnt(0)
	v_mfma_f32_16x16x32_bf16 v[124:127], v[152:155], v[192:195], v[124:127]
	v_mfma_f32_16x16x32_bf16 v[120:123], v[160:163], v[192:195], v[120:123]
	v_mfma_f32_16x16x32_bf16 v[108:111], v[152:155], v[200:203], v[108:111]
	v_mfma_f32_16x16x32_bf16 v[104:107], v[160:163], v[200:203], v[104:107]
	v_mfma_f32_16x16x32_bf16 v[92:95], v[152:155], v[208:211], v[92:95]
	v_mfma_f32_16x16x32_bf16 v[88:91], v[160:163], v[208:211], v[88:91]
	v_mfma_f32_16x16x32_bf16 v[76:79], v[152:155], v[216:219], v[76:79]
	v_mfma_f32_16x16x32_bf16 v[72:75], v[160:163], v[216:219], v[72:75]
	v_mfma_f32_16x16x32_bf16 v[124:127], v[156:159], v[196:199], v[124:127]
	v_mfma_f32_16x16x32_bf16 v[120:123], v[164:167], v[196:199], v[120:123]
	v_mfma_f32_16x16x32_bf16 v[108:111], v[156:159], v[204:207], v[108:111]
	v_mfma_f32_16x16x32_bf16 v[104:107], v[164:167], v[204:207], v[104:107]
	v_mfma_f32_16x16x32_bf16 v[92:95], v[156:159], v[212:215], v[92:95]
	v_mfma_f32_16x16x32_bf16 v[88:91], v[164:167], v[212:215], v[88:91]
	v_mfma_f32_16x16x32_bf16 v[76:79], v[156:159], v[240:243], v[76:79]
	v_mfma_f32_16x16x32_bf16 v[72:75], v[164:167], v[240:243], v[72:75]
	s_setprio 0
	s_setprio 1
	v_mfma_f32_16x16x32_bf16 v[116:119], v[176:179], v[192:195], v[116:119]
	v_mfma_f32_16x16x32_bf16 v[112:115], v[184:187], v[192:195], v[112:115]
	v_mfma_f32_16x16x32_bf16 v[100:103], v[176:179], v[200:203], v[100:103]
	v_mfma_f32_16x16x32_bf16 v[96:99], v[184:187], v[200:203], v[96:99]
	v_mfma_f32_16x16x32_bf16 v[84:87], v[176:179], v[208:211], v[84:87]
	v_mfma_f32_16x16x32_bf16 v[80:83], v[184:187], v[208:211], v[80:83]
	v_mfma_f32_16x16x32_bf16 v[68:71], v[176:179], v[216:219], v[68:71]
	v_mfma_f32_16x16x32_bf16 v[64:67], v[184:187], v[216:219], v[64:67]
	v_mfma_f32_16x16x32_bf16 v[116:119], v[180:183], v[196:199], v[116:119]
	v_mfma_f32_16x16x32_bf16 v[112:115], v[188:191], v[196:199], v[112:115]
	v_mfma_f32_16x16x32_bf16 v[100:103], v[180:183], v[204:207], v[100:103]
	v_mfma_f32_16x16x32_bf16 v[96:99], v[188:191], v[204:207], v[96:99]
	v_mfma_f32_16x16x32_bf16 v[84:87], v[180:183], v[212:215], v[84:87]
	v_mfma_f32_16x16x32_bf16 v[80:83], v[188:191], v[212:215], v[80:83]
	v_mfma_f32_16x16x32_bf16 v[68:71], v[180:183], v[240:243], v[68:71]
	v_mfma_f32_16x16x32_bf16 v[64:67], v[188:191], v[240:243], v[64:67]
	s_setprio 0
	s_barrier
	s_add_i32 s10, s10, s45
	v_lshl_add_u64 v[146:147], v[244:245], 0, s[92:93]
	s_mov_b32 m0, s10
	ds_read_b128 v[192:195], v151 offset:49152
	ds_read_b128 v[196:199], v151 offset:50176
	ds_read_b128 v[200:203], v151 offset:51200
	ds_read_b128 v[204:207], v151 offset:52224
	ds_read_b128 v[208:211], v151 offset:53248
	ds_read_b128 v[212:215], v151 offset:54272
	ds_read_b128 v[216:219], v151 offset:55296
	ds_read_b128 v[240:243], v151 offset:56320
	global_load_lds_dwordx4 v[146:147], off
	v_lshl_add_u64 v[146:147], v[246:247], 0, s[92:93]
	s_add_i32 m0, s10, 0x2000
	s_add_i32 s10, s62, s45
	global_load_lds_dwordx4 v[146:147], off
	v_lshl_add_u64 v[146:147], v[248:249], 0, s[92:93]
	s_mov_b32 m0, s10
	s_nop 0
	global_load_lds_dwordx4 v[146:147], off
	v_lshl_add_u64 v[146:147], v[220:221], 0, s[92:93]
	s_add_i32 m0, s10, 0x2000
	s_nop 0
	global_load_lds_dwordx4 v[146:147], off
	v_lshl_add_u64 v[146:147], v[250:251], 0, s[92:93]
	s_mov_b32 m0, s53
	s_nop 0
	global_load_lds_dwordx4 v[146:147], off
	v_lshl_add_u64 v[146:147], v[252:253], 0, s[92:93]
	s_mov_b32 m0, s54
	s_nop 0
	global_load_lds_dwordx4 v[146:147], off
	s_waitcnt vmcnt(8)
	s_waitcnt lgkmcnt(0)
	s_barrier
	s_setprio 1
	s_waitcnt lgkmcnt(0)
	v_mfma_f32_16x16x32_bf16 v[60:63], v[152:155], v[192:195], v[60:63]
	v_mfma_f32_16x16x32_bf16 v[56:59], v[160:163], v[192:195], v[56:59]
	v_mfma_f32_16x16x32_bf16 v[44:47], v[152:155], v[200:203], v[44:47]
	v_mfma_f32_16x16x32_bf16 v[40:43], v[160:163], v[200:203], v[40:43]
	v_mfma_f32_16x16x32_bf16 v[28:31], v[152:155], v[208:211], v[28:31]
	v_mfma_f32_16x16x32_bf16 v[24:27], v[160:163], v[208:211], v[24:27]
	v_mfma_f32_16x16x32_bf16 v[12:15], v[152:155], v[216:219], v[12:15]
	v_mfma_f32_16x16x32_bf16 v[8:11], v[160:163], v[216:219], v[8:11]
	v_mfma_f32_16x16x32_bf16 v[60:63], v[156:159], v[196:199], v[60:63]
	v_mfma_f32_16x16x32_bf16 v[56:59], v[164:167], v[196:199], v[56:59]
	v_mfma_f32_16x16x32_bf16 v[44:47], v[156:159], v[204:207], v[44:47]
	v_mfma_f32_16x16x32_bf16 v[40:43], v[164:167], v[204:207], v[40:43]
	v_mfma_f32_16x16x32_bf16 v[28:31], v[156:159], v[212:215], v[28:31]
	v_mfma_f32_16x16x32_bf16 v[24:27], v[164:167], v[212:215], v[24:27]
	v_mfma_f32_16x16x32_bf16 v[12:15], v[156:159], v[240:243], v[12:15]
	v_mfma_f32_16x16x32_bf16 v[8:11], v[164:167], v[240:243], v[8:11]
	s_setprio 0
	s_setprio 1
	v_mfma_f32_16x16x32_bf16 v[52:55], v[176:179], v[192:195], v[52:55]
	v_mfma_f32_16x16x32_bf16 v[48:51], v[184:187], v[192:195], v[48:51]
	v_mfma_f32_16x16x32_bf16 v[36:39], v[176:179], v[200:203], v[36:39]
	v_mfma_f32_16x16x32_bf16 v[32:35], v[184:187], v[200:203], v[32:35]
	v_mfma_f32_16x16x32_bf16 v[20:23], v[176:179], v[208:211], v[20:23]
	v_mfma_f32_16x16x32_bf16 v[16:19], v[184:187], v[208:211], v[16:19]
	v_mfma_f32_16x16x32_bf16 v[4:7], v[176:179], v[216:219], v[4:7]
	v_mfma_f32_16x16x32_bf16 v[0:3], v[184:187], v[216:219], v[0:3]
	v_mfma_f32_16x16x32_bf16 v[52:55], v[180:183], v[196:199], v[52:55]
	v_mfma_f32_16x16x32_bf16 v[48:51], v[188:191], v[196:199], v[48:51]
	v_mfma_f32_16x16x32_bf16 v[36:39], v[180:183], v[204:207], v[36:39]
	v_mfma_f32_16x16x32_bf16 v[32:35], v[188:191], v[204:207], v[32:35]
	v_mfma_f32_16x16x32_bf16 v[20:23], v[180:183], v[212:215], v[20:23]
	v_mfma_f32_16x16x32_bf16 v[16:19], v[188:191], v[212:215], v[16:19]
	v_mfma_f32_16x16x32_bf16 v[4:7], v[180:183], v[240:243], v[4:7]
	v_mfma_f32_16x16x32_bf16 v[0:3], v[188:191], v[240:243], v[0:3]
	s_setprio 0
	s_barrier
	v_lshl_add_u64 v[142:143], v[142:143], 0, s[80:81]
	v_lshl_add_u64 v[144:145], v[144:145], 0, s[80:81]
	s_mov_b32 s10, s11
	s_cmp_eq_u32 s10, s55
	s_cbranch_scc1 .Lq5_last
	s_branch .LBB0_354

; #define PG8_STAGE(bufoff, gbase, voff) do { _Pragma("unroll") for (int _i = 0; _i < 2; ++_i) \
;         __builtin_amdgcn_global_load_lds((const unsigned*)((const char*)(gbase) + (voff)[_i]), (LAS unsigned*)(lds + (bufoff) + ldsw + _i * 8192), 16, 0, 0); } while (0)
; #define PG8_LDA(dst, b, h) do { _Pragma("unroll") for (int m = 0; m < 4; ++m) _Pragma("unroll") for (int k = 0; k < 2; ++k) dst[m][k] = *(const LAS bf16x8*)(lds + PG8_SA(b, h) + aoff + m * 2048 + k * 1024); } while (0)
; #define PG8_LDB(dst, b, h) do { _Pragma("unroll") for (int n = 0; n < 2; ++n) _Pragma("unroll") for (int k = 0; k < 2; ++k) dst[n][k] = *(const LAS bf16x8*)(lds + PG8_SB(b, h) + boff + n * 2048 + k * 1024); } while (0)
; #define PG8_MMA(ai, bj, At, Bt) do { __builtin_amdgcn_s_setprio(1); _Pragma("unroll") for (int k = 0; k < 2; ++k) _Pragma("unroll") for (int m = 0; m < 4; ++m) _Pragma("unroll") for (int n = 0; n < 2; ++n) \
;         acc[ai][bj][m][n] = __builtin_amdgcn_mfma_f32_16x16x32_bf16(Bt[n][k], At[m][k], acc[ai][bj][m][n], 0, 0, 0); __builtin_amdgcn_s_setprio(0); } while (0)
; #define PG8_WAIT_V(n) asm volatile("s_waitcnt vmcnt(" #n ")" ::: "memory")
; #define PG8_WAIT_L(n) asm volatile("s_waitcnt lgkmcnt(" #n ")" ::: "memory")
; #define PG8_BAR __builtin_amdgcn_s_barrier()
; #define PG8_SCHED __builtin_amdgcn_sched_barrier(0)
; template <class Epi, bool ALIGN_EPI>
; __device__ __forceinline__ void gemm_phase(LAS unsigned char* lds, const Gemm g, const StaticOrder& S, const Epi& E, const int tid) {
;     ...
;             PG8_LDB(B0, 0, 0); PG8_LDB(B1, 0, 1); PG8_SCHED; PG8_LDA(At, 0, 0); PG8_STAGE(PG8_SA(1, 1), a1 + hA, voffA);
;             PG8_WAIT_V(8); PG8_WAIT_L(0); PG8_BAR; PG8_MMA(0, 0, At, B0); PG8_MMA(0, 1, At, B1); PG8_BAR; PG8_SCHED;
;             PG8_LDA(At, 0, 1); PG8_STAGE(PG8_SB(0, 0), b2, voffB); PG8_STAGE(PG8_SB(0, 1), b2 + hB, voffB); PG8_STAGE(PG8_SA(0, 0), a2, voffA);
;             PG8_WAIT_V(8); PG8_WAIT_L(0); PG8_BAR; PG8_MMA(1, 0, At, B0); PG8_MMA(1, 1, At, B1); PG8_BAR; PG8_SCHED;
.Lq5_last:
	s_add_i32 s11, s10, 2
	s_cmp_eq_u32 s55, s10
	s_cselect_b64 vcc, -1, 0
	v_add_u32_e32 v148, s33, v149
	s_add_i32 s10, 0, 0x14000
	ds_read_b128 v[152:155], v148
	ds_read_b128 v[156:159], v148 offset:1024
	ds_read_b128 v[160:163], v148 offset:2048
	ds_read_b128 v[164:167], v148 offset:3072
	v_add_u32_e32 v148, s10, v149
	ds_read_b128 v[176:179], v148
	ds_read_b128 v[180:183], v148 offset:1024
	ds_read_b128 v[184:187], v148 offset:2048
	ds_read_b128 v[188:191], v148 offset:3072
	v_lshl_add_u64 v[146:147], v[142:143], 0, s[92:93]
	v_cndmask_b32_e32 v147, v147, v139, vcc
	v_cndmask_b32_e32 v146, v146, v138, vcc
	v_cndmask_b32_e32 v221, v145, v141, vcc
	v_cndmask_b32_e32 v220, v144, v140, vcc
	v_lshl_add_u64 v[244:245], v[142:143], 0, v[134:135]
	s_add_i32 m0, s25, 0xc000
	ds_read_b128 v[192:195], v151
	ds_read_b128 v[196:199], v151 offset:1024
	ds_read_b128 v[200:203], v151 offset:2048
	ds_read_b128 v[204:207], v151 offset:3072
	ds_read_b128 v[208:211], v151 offset:4096
	ds_read_b128 v[212:215], v151 offset:5120
	ds_read_b128 v[216:219], v151 offset:6144
	ds_read_b128 v[240:243], v151 offset:7168
	global_load_lds_dwordx4 v[244:245], off
	v_lshl_add_u64 v[244:245], v[142:143], 0, v[136:137]
	s_add_i32 m0, s25, 0xe000
	s_nop 0
	global_load_lds_dwordx4 v[244:245], off
	s_waitcnt vmcnt(8)
	s_waitcnt lgkmcnt(0)
	s_barrier
	s_setprio 1
	s_waitcnt lgkmcnt(0)
	v_mfma_f32_16x16x32_bf16 v[124:127], v[152:155], v[192:195], v[124:127]
	v_mfma_f32_16x16x32_bf16 v[120:123], v[160:163], v[192:195], v[120:123]
	v_mfma_f32_16x16x32_bf16 v[108:111], v[152:155], v[200:203], v[108:111]
	v_mfma_f32_16x16x32_bf16 v[104:107], v[160:163], v[200:203], v[104:107]
	v_mfma_f32_16x16x32_bf16 v[92:95], v[152:155], v[208:211], v[92:95]
	v_mfma_f32_16x16x32_bf16 v[88:91], v[160:163], v[208:211], v[88:91]
	v_mfma_f32_16x16x32_bf16 v[76:79], v[152:155], v[216:219], v[76:79]
	v_mfma_f32_16x16x32_bf16 v[72:75], v[160:163], v[216:219], v[72:75]
	v_mfma_f32_16x16x32_bf16 v[124:127], v[156:159], v[196:199], v[124:127]
	v_mfma_f32_16x16x32_bf16 v[120:123], v[164:167], v[196:199], v[120:123]
	v_mfma_f32_16x16x32_bf16 v[108:111], v[156:159], v[204:207], v[108:111]
	v_mfma_f32_16x16x32_bf16 v[104:107], v[164:167], v[204:207], v[104:107]
	v_mfma_f32_16x16x32_bf16 v[92:95], v[156:159], v[212:215], v[92:95]
	v_mfma_f32_16x16x32_bf16 v[88:91], v[164:167], v[212:215], v[88:91]
	v_mfma_f32_16x16x32_bf16 v[76:79], v[156:159], v[240:243], v[76:79]
	v_mfma_f32_16x16x32_bf16 v[72:75], v[164:167], v[240:243], v[72:75]
	s_setprio 0
	s_setprio 1
	v_mfma_f32_16x16x32_bf16 v[116:119], v[176:179], v[192:195], v[116:119]
	v_mfma_f32_16x16x32_bf16 v[112:115], v[184:187], v[192:195], v[112:115]
	v_mfma_f32_16x16x32_bf16 v[100:103], v[176:179], v[200:203], v[100:103]
	v_mfma_f32_16x16x32_bf16 v[96:99], v[184:187], v[200:203], v[96:99]
	v_mfma_f32_16x16x32_bf16 v[84:87], v[176:179], v[208:211], v[84:87]
	v_mfma_f32_16x16x32_bf16 v[80:83], v[184:187], v[208:211], v[80:83]
	v_mfma_f32_16x16x32_bf16 v[68:71], v[176:179], v[216:219], v[68:71]
	v_mfma_f32_16x16x32_bf16 v[64:67], v[184:187], v[216:219], v[64:67]
	v_mfma_f32_16x16x32_bf16 v[116:119], v[180:183], v[196:199], v[116:119]
	v_mfma_f32_16x16x32_bf16 v[112:115], v[188:191], v[196:199], v[112:115]
	v_mfma_f32_16x16x32_bf16 v[100:103], v[180:183], v[204:207], v[100:103]
	v_mfma_f32_16x16x32_bf16 v[96:99], v[188:191], v[204:207], v[96:99]
	v_mfma_f32_16x16x32_bf16 v[84:87], v[180:183], v[212:215], v[84:87]
	v_mfma_f32_16x16x32_bf16 v[80:83], v[188:191], v[212:215], v[80:83]
	v_mfma_f32_16x16x32_bf16 v[68:71], v[180:183], v[240:243], v[68:71]
	v_mfma_f32_16x16x32_bf16 v[64:67], v[188:191], v[240:243], v[64:67]
	s_setprio 0
	s_barrier
	s_add_i32 s62, s33, s45
	v_lshl_add_u64 v[244:245], v[220:221], 0, v[168:169]
	s_mov_b32 m0, s62
	ds_read_b128 v[192:195], v151 offset:16384
	ds_read_b128 v[196:199], v151 offset:17408
	ds_read_b128 v[200:203], v151 offset:18432
	ds_read_b128 v[204:207], v151 offset:19456
	ds_read_b128 v[208:211], v151 offset:20480
	ds_read_b128 v[212:215], v151 offset:21504
	ds_read_b128 v[216:219], v151 offset:22528
	ds_read_b128 v[240:243], v151 offset:23552
	global_load_lds_dwordx4 v[244:245], off
	v_lshl_add_u64 v[246:247], v[220:221], 0, v[128:129]
	s_add_i32 m0, s62, 0x2000
	v_lshl_add_u64 v[220:221], v[220:221], 0, s[12:13]
	s_add_i32 s10, s10, s45
	global_load_lds_dwordx4 v[246:247], off
	v_lshl_add_u64 v[248:249], v[220:221], 0, v[168:169]
	s_mov_b32 m0, s10
	v_lshl_add_u64 v[220:221], v[220:221], 0, v[128:129]
	global_load_lds_dwordx4 v[248:249], off
	s_add_i32 m0, s10, 0x2000
	v_lshl_add_u64 v[250:251], v[146:147], 0, v[132:133]
	global_load_lds_dwordx4 v[220:221], off
	s_mov_b32 m0, s25
	v_lshl_add_u64 v[252:253], v[146:147], 0, v[130:131]
	global_load_lds_dwordx4 v[250:251], off
	s_mov_b32 m0, s50
	s_nop 0
	global_load_lds_dwordx4 v[252:253], off
	s_waitcnt vmcnt(8)
	s_waitcnt lgkmcnt(0)
	s_barrier
; #define PG8_STAGE(bufoff, gbase, voff) do { _Pragma("unroll") for (int _i = 0; _i < 2; ++_i) \
;         __builtin_amdgcn_global_load_lds((const unsigned*)((const char*)(gbase) + (voff)[_i]), (LAS unsigned*)(lds + (bufoff) + ldsw + _i * 8192), 16, 0, 0); } while (0)
; #define PG8_LDA(dst, b, h) do { _Pragma("unroll") for (int m = 0; m < 4; ++m) _Pragma("unroll") for (int k = 0; k < 2; ++k) dst[m][k] = *(const LAS bf16x8*)(lds + PG8_SA(b, h) + aoff + m * 2048 + k * 1024); } while (0)
; #define PG8_LDB(dst, b, h) do { _Pragma("unroll") for (int n = 0; n < 2; ++n) _Pragma("unroll") for (int k = 0; k < 2; ++k) dst[n][k] = *(const LAS bf16x8*)(lds + PG8_SB(b, h) + boff + n * 2048 + k * 1024); } while (0)
; #define PG8_MMA(ai, bj, At, Bt) do { __builtin_amdgcn_s_setprio(1); _Pragma("unroll") for (int k = 0; k < 2; ++k) _Pragma("unroll") for (int m = 0; m < 4; ++m) _Pragma("unroll") for (int n = 0; n < 2; ++n) \
;         acc[ai][bj][m][n] = __builtin_amdgcn_mfma_f32_16x16x32_bf16(Bt[n][k], At[m][k], acc[ai][bj][m][n], 0, 0, 0); __builtin_amdgcn_s_setprio(0); } while (0)
; #define PG8_WAIT_V(n) asm volatile("s_waitcnt vmcnt(" #n ")" ::: "memory")
; #define PG8_WAIT_L(n) asm volatile("s_waitcnt lgkmcnt(" #n ")" ::: "memory")
; #define PG8_BAR __builtin_amdgcn_s_barrier()
; #define PG8_SCHED __builtin_amdgcn_sched_barrier(0)
; template <class Epi, bool ALIGN_EPI>
; __device__ __forceinline__ void gemm_phase(LAS unsigned char* lds, const Gemm g, const StaticOrder& S, const Epi& E, const int tid) {
;     ...
;             PG8_WAIT_V(8); PG8_WAIT_L(0); PG8_BAR; PG8_MMA(1, 0, At, B0); PG8_MMA(1, 1, At, B1); PG8_BAR; PG8_SCHED;
;             PG8_LDB(B0, 1, 0); PG8_LDB(B1, 1, 1); PG8_SCHED; PG8_LDA(At, 1, 0); PG8_STAGE(PG8_SA(0, 1), a2 + hA, voffA);
;             PG8_WAIT_V(8); PG8_WAIT_L(0); PG8_BAR; PG8_MMA(0, 0, At, B0); PG8_MMA(0, 1, At, B1); PG8_BAR; PG8_SCHED;
;             PG8_LDA(At, 1, 1); PG8_STAGE(PG8_SB(1, 0), b3, voffB); PG8_STAGE(PG8_SB(1, 1), b3 + hB, voffB); PG8_STAGE(PG8_SA(1, 0), a3, voffA);
	s_setprio 1
	s_waitcnt lgkmcnt(0)
	v_mfma_f32_16x16x32_bf16 v[60:63], v[152:155], v[192:195], v[60:63]
	v_mfma_f32_16x16x32_bf16 v[56:59], v[160:163], v[192:195], v[56:59]
	v_mfma_f32_16x16x32_bf16 v[44:47], v[152:155], v[200:203], v[44:47]
	v_mfma_f32_16x16x32_bf16 v[40:43], v[160:163], v[200:203], v[40:43]
	v_mfma_f32_16x16x32_bf16 v[28:31], v[152:155], v[208:211], v[28:31]
	v_mfma_f32_16x16x32_bf16 v[24:27], v[160:163], v[208:211], v[24:27]
	v_mfma_f32_16x16x32_bf16 v[12:15], v[152:155], v[216:219], v[12:15]
	v_mfma_f32_16x16x32_bf16 v[8:11], v[160:163], v[216:219], v[8:11]
	v_mfma_f32_16x16x32_bf16 v[60:63], v[156:159], v[196:199], v[60:63]
	v_mfma_f32_16x16x32_bf16 v[56:59], v[164:167], v[196:199], v[56:59]
	v_mfma_f32_16x16x32_bf16 v[44:47], v[156:159], v[204:207], v[44:47]
	v_mfma_f32_16x16x32_bf16 v[40:43], v[164:167], v[204:207], v[40:43]
	v_mfma_f32_16x16x32_bf16 v[28:31], v[156:159], v[212:215], v[28:31]
	v_mfma_f32_16x16x32_bf16 v[24:27], v[164:167], v[212:215], v[24:27]
	v_mfma_f32_16x16x32_bf16 v[12:15], v[156:159], v[240:243], v[12:15]
	v_mfma_f32_16x16x32_bf16 v[8:11], v[164:167], v[240:243], v[8:11]
	s_setprio 0
	s_setprio 1
	v_mfma_f32_16x16x32_bf16 v[52:55], v[176:179], v[192:195], v[52:55]
	v_mfma_f32_16x16x32_bf16 v[48:51], v[184:187], v[192:195], v[48:51]
	v_mfma_f32_16x16x32_bf16 v[36:39], v[176:179], v[200:203], v[36:39]
	v_mfma_f32_16x16x32_bf16 v[32:35], v[184:187], v[200:203], v[32:35]
	v_mfma_f32_16x16x32_bf16 v[20:23], v[176:179], v[208:211], v[20:23]
	v_mfma_f32_16x16x32_bf16 v[16:19], v[184:187], v[208:211], v[16:19]
	v_mfma_f32_16x16x32_bf16 v[4:7], v[176:179], v[216:219], v[4:7]
	v_mfma_f32_16x16x32_bf16 v[0:3], v[184:187], v[216:219], v[0:3]
	v_mfma_f32_16x16x32_bf16 v[52:55], v[180:183], v[196:199], v[52:55]
	v_mfma_f32_16x16x32_bf16 v[48:51], v[188:191], v[196:199], v[48:51]
	v_mfma_f32_16x16x32_bf16 v[36:39], v[180:183], v[204:207], v[36:39]
	v_mfma_f32_16x16x32_bf16 v[32:35], v[188:191], v[204:207], v[32:35]
	v_mfma_f32_16x16x32_bf16 v[20:23], v[180:183], v[212:215], v[20:23]
	v_mfma_f32_16x16x32_bf16 v[16:19], v[188:191], v[212:215], v[16:19]
	v_mfma_f32_16x16x32_bf16 v[4:7], v[180:183], v[240:243], v[4:7]
	v_mfma_f32_16x16x32_bf16 v[0:3], v[188:191], v[240:243], v[0:3]
	s_setprio 0
	s_barrier
	s_add_i32 s10, 0, 0x18000
	v_add_u32_e32 v148, s10, v149
	s_add_i32 s62, 0, 0x1c000
	ds_read_b128 v[152:155], v148
	ds_read_b128 v[156:159], v148 offset:1024
	ds_read_b128 v[160:163], v148 offset:2048
	ds_read_b128 v[164:167], v148 offset:3072
	v_add_u32_e32 v148, s62, v149
	ds_read_b128 v[176:179], v148
	ds_read_b128 v[180:183], v148 offset:1024
	ds_read_b128 v[184:187], v148 offset:2048
	ds_read_b128 v[188:191], v148 offset:3072
	v_lshl_add_u64 v[146:147], v[146:147], 0, s[94:95]
	s_mov_b32 m0, s51
	v_lshl_add_u64 v[226:227], v[146:147], 0, v[132:133]
	ds_read_b128 v[192:195], v151 offset:32768
	ds_read_b128 v[196:199], v151 offset:33792
	ds_read_b128 v[200:203], v151 offset:34816
	ds_read_b128 v[204:207], v151 offset:35840
	ds_read_b128 v[208:211], v151 offset:36864
	ds_read_b128 v[212:215], v151 offset:37888
	ds_read_b128 v[216:219], v151 offset:38912
	ds_read_b128 v[240:243], v151 offset:39936
	global_load_lds_dwordx4 v[226:227], off
	v_lshl_add_u64 v[146:147], v[146:147], 0, v[130:131]
	s_mov_b32 m0, s52
	s_nop 0
	global_load_lds_dwordx4 v[146:147], off
	s_waitcnt vmcnt(8)
	s_waitcnt lgkmcnt(0)
	s_barrier
	s_setprio 1
	s_waitcnt lgkmcnt(0)
	v_mfma_f32_16x16x32_bf16 v[124:127], v[152:155], v[192:195], v[124:127]
	v_mfma_f32_16x16x32_bf16 v[120:123], v[160:163], v[192:195], v[120:123]
	v_mfma_f32_16x16x32_bf16 v[108:111], v[152:155], v[200:203], v[108:111]
	v_mfma_f32_16x16x32_bf16 v[104:107], v[160:163], v[200:203], v[104:107]
	v_mfma_f32_16x16x32_bf16 v[92:95], v[152:155], v[208:211], v[92:95]
	v_mfma_f32_16x16x32_bf16 v[88:91], v[160:163], v[208:211], v[88:91]
	v_mfma_f32_16x16x32_bf16 v[76:79], v[152:155], v[216:219], v[76:79]
	v_mfma_f32_16x16x32_bf16 v[72:75], v[160:163], v[216:219], v[72:75]
	v_mfma_f32_16x16x32_bf16 v[124:127], v[156:159], v[196:199], v[124:127]
	v_mfma_f32_16x16x32_bf16 v[120:123], v[164:167], v[196:199], v[120:123]
	v_mfma_f32_16x16x32_bf16 v[108:111], v[156:159], v[204:207], v[108:111]
	v_mfma_f32_16x16x32_bf16 v[104:107], v[164:167], v[204:207], v[104:107]
	v_mfma_f32_16x16x32_bf16 v[92:95], v[156:159], v[212:215], v[92:95]
	v_mfma_f32_16x16x32_bf16 v[88:91], v[164:167], v[212:215], v[88:91]
	v_mfma_f32_16x16x32_bf16 v[76:79], v[156:159], v[240:243], v[76:79]
	v_mfma_f32_16x16x32_bf16 v[72:75], v[164:167], v[240:243], v[72:75]
	s_setprio 0
	s_setprio 1
	v_mfma_f32_16x16x32_bf16 v[116:119], v[176:179], v[192:195], v[116:119]
	v_mfma_f32_16x16x32_bf16 v[112:115], v[184:187], v[192:195], v[112:115]
	v_mfma_f32_16x16x32_bf16 v[100:103], v[176:179], v[200:203], v[100:103]
	v_mfma_f32_16x16x32_bf16 v[96:99], v[184:187], v[200:203], v[96:99]
	v_mfma_f32_16x16x32_bf16 v[84:87], v[176:179], v[208:211], v[84:87]
	v_mfma_f32_16x16x32_bf16 v[80:83], v[184:187], v[208:211], v[80:83]
	v_mfma_f32_16x16x32_bf16 v[68:71], v[176:179], v[216:219], v[68:71]
	v_mfma_f32_16x16x32_bf16 v[64:67], v[184:187], v[216:219], v[64:67]
	v_mfma_f32_16x16x32_bf16 v[116:119], v[180:183], v[196:199], v[116:119]
	v_mfma_f32_16x16x32_bf16 v[112:115], v[188:191], v[196:199], v[112:115]
	v_mfma_f32_16x16x32_bf16 v[100:103], v[180:183], v[204:207], v[100:103]
	v_mfma_f32_16x16x32_bf16 v[96:99], v[188:191], v[204:207], v[96:99]
	v_mfma_f32_16x16x32_bf16 v[84:87], v[180:183], v[212:215], v[84:87]
	v_mfma_f32_16x16x32_bf16 v[80:83], v[188:191], v[212:215], v[80:83]
	v_mfma_f32_16x16x32_bf16 v[68:71], v[180:183], v[240:243], v[68:71]
	v_mfma_f32_16x16x32_bf16 v[64:67], v[188:191], v[240:243], v[64:67]
	s_setprio 0
	s_barrier
; __device__ __forceinline__ unsigned cvt_pk_bf16(float lo, float hi) { unsigned r; asm volatile("v_cvt_pk_bf16_f32 %0, %1, %2" : "=v"(r) : "v"(lo), "v"(hi)); return r; }
; __device__ __forceinline__ float gelu_tanh(float x) { const float u = 0.7978845608028654f * (x + 0.044715f * x * x * x); return x * fast_rcp(1.0f + fast_exp2(-2.0f * LOG2E * u)); }
; #define PG8_STAGE(bufoff, gbase, voff) do { _Pragma("unroll") for (int _i = 0; _i < 2; ++_i) \
;         __builtin_amdgcn_global_load_lds((const unsigned*)((const char*)(gbase) + (voff)[_i]), (LAS unsigned*)(lds + (bufoff) + ldsw + _i * 8192), 16, 0, 0); } while (0)
; #define PG8_LDA(dst, b, h) do { _Pragma("unroll") for (int m = 0; m < 4; ++m) _Pragma("unroll") for (int k = 0; k < 2; ++k) dst[m][k] = *(const LAS bf16x8*)(lds + PG8_SA(b, h) + aoff + m * 2048 + k * 1024); } while (0)
; #define PG8_WAIT_V(n) asm volatile("s_waitcnt vmcnt(" #n ")" ::: "memory")
;     __device__ __forceinline__ void operator()(const f32x4 (&acc)[2][2][4][2], const Unit& u, int wr, int wc, int fr, int fq) const {
;         const int row0 = u.pm * BM + wr * 64 + fr, col0 = u.pn * BM + wc * 32 + 8 * fq;
;         float rsv[2][4]; load_rstd(rsv, ssq, row0);
; #pragma unroll
;         for (int ai = 0; ai < 2; ++ai)
; #pragma unroll
;             for (int m = 0; m < 4; ++m) { const int row = row0 + ai * HALF + m * 16; bf16_t* rowp = O + (size_t)row * ldc + col0; const float rs = rsv[ai][m];
; #pragma unroll
;                 for (int bj = 0; bj < 2; ++bj) { f32x4 v0 = acc[ai][bj][m][0] * rs, v1 = acc[ai][bj][m][1] * rs;
;                     if (ACT == 1) {
; #pragma unroll
;                         for (int j = 0; j < 4; ++j) { v0[j] = gelu_tanh(v0[j]); v1[j] = gelu_tanh(v1[j]); } }
;                     u32x4 w; w.x = cvt_pk_bf16(v0[0], v0[1]); w.y = cvt_pk_bf16(v0[2], v0[3]); w.z = cvt_pk_bf16(v1[0], v1[1]); w.w = cvt_pk_bf16(v1[2], v1[3]);
;                     *(u32x4*)(rowp + bj * HALF) = w; } }
; template <class Epi, bool ALIGN_EPI>
; __device__ __forceinline__ void gemm_phase(LAS unsigned char* lds, const Gemm g, const StaticOrder& S, const Epi& E, const int tid) {
;     ...
;             PG8_LDA(At, 1, 1); PG8_STAGE(PG8_SB(1, 0), b3, voffB); PG8_STAGE(PG8_SB(1, 1), b3 + hB, voffB); PG8_STAGE(PG8_SA(1, 0), a3, voffA);
;             PG8_WAIT_V(8); PG8_WAIT_L(0); PG8_BAR; PG8_MMA(1, 0, At, B0); PG8_MMA(1, 1, At, B1); PG8_BAR; PG8_SCHED;
	s_add_i32 s10, s10, s45
	v_lshl_add_u64 v[146:147], v[244:245], 0, s[92:93]
	s_mov_b32 m0, s10
	ds_read_b128 v[192:195], v151 offset:49152
	ds_read_b128 v[196:199], v151 offset:50176
	ds_read_b128 v[200:203], v151 offset:51200
	ds_read_b128 v[204:207], v151 offset:52224
	ds_read_b128 v[208:211], v151 offset:53248
	ds_read_b128 v[212:215], v151 offset:54272
	ds_read_b128 v[216:219], v151 offset:55296
	ds_read_b128 v[240:243], v151 offset:56320
	global_load_lds_dwordx4 v[146:147], off
	v_lshl_add_u64 v[146:147], v[246:247], 0, s[92:93]
	s_add_i32 m0, s10, 0x2000
	s_add_i32 s10, s62, s45
	global_load_lds_dwordx4 v[146:147], off
	v_lshl_add_u64 v[146:147], v[248:249], 0, s[92:93]
	s_mov_b32 m0, s10
	s_nop 0
	global_load_lds_dwordx4 v[146:147], off
	v_lshl_add_u64 v[146:147], v[220:221], 0, s[92:93]
	s_add_i32 m0, s10, 0x2000
	s_nop 0
	global_load_lds_dwordx4 v[146:147], off
	v_lshl_add_u64 v[146:147], v[250:251], 0, s[92:93]
	s_mov_b32 m0, s53
	s_nop 0
	global_load_lds_dwordx4 v[146:147], off
	v_lshl_add_u64 v[146:147], v[252:253], 0, s[92:93]
	s_mov_b32 m0, s54
	s_nop 0
	global_load_lds_dwordx4 v[146:147], off
	s_waitcnt vmcnt(8)
	s_waitcnt lgkmcnt(0)
	s_barrier
	s_setprio 1
	s_waitcnt lgkmcnt(0)
	v_mfma_f32_16x16x32_bf16 v[60:63], v[152:155], v[192:195], v[60:63]
	v_lshrrev_b32_e32 v171, 8, v170
	v_and_b32_e32 v234, 15, v170
	v_lshl_add_u32 v171, v171, 6, v234
	s_lshl_b32 s98, s61, 8
	v_add_u32_e32 v171, s98, v171
	v_mfma_f32_16x16x32_bf16 v[56:59], v[160:163], v[192:195], v[56:59]
	v_mul_lo_u32 v171, v171, s28
	v_bfe_u32 v234, v170, 6, 2
	v_bfe_u32 v224, v170, 4, 2
	v_lshlrev_b32_e32 v234, 5, v234
	v_lshl_or_b32 v234, v224, 3, v234
	v_mfma_f32_16x16x32_bf16 v[44:47], v[152:155], v[200:203], v[44:47]
	s_lshl_b32 s98, s60, 8
	v_add_u32_e32 v234, s98, v234
	v_add_lshl_u32 v232, v171, v234, 1
	v_mov_b32_e32 v233, 0
	v_lshl_add_u64 v[232:233], v[232:233], 0, s[30:31]
	v_mfma_f32_16x16x32_bf16 v[40:43], v[160:163], v[200:203], v[40:43]
	s_lshl_b32 s98, s28, 5
	s_mov_b32 s99, 0
	v_mul_f32_e32 v124, v172, v124
	v_mul_f32_e32 v125, v172, v125
	v_mul_f32_e32 v126, v172, v126
	v_mfma_f32_16x16x32_bf16 v[28:31], v[152:155], v[208:211], v[28:31]
	v_mul_f32_e32 v127, v172, v127
	v_mul_f32_e32 v120, v172, v120
	v_mul_f32_e32 v121, v172, v121
	v_mul_f32_e32 v122, v172, v122
	v_mul_f32_e32 v123, v172, v123
	v_mfma_f32_16x16x32_bf16 v[24:27], v[160:163], v[208:211], v[24:27]
	v_cvt_pk_bf16_f32 v124, v124, v125
	v_cvt_pk_bf16_f32 v125, v126, v127
	v_cvt_pk_bf16_f32 v126, v120, v121
	v_cvt_pk_bf16_f32 v127, v122, v123
	global_store_dwordx4 v[232:233], v[124:127], off
	v_mfma_f32_16x16x32_bf16 v[12:15], v[152:155], v[216:219], v[12:15]
	v_mul_f32_e32 v116, v172, v116
	v_mul_f32_e32 v117, v172, v117
	v_mul_f32_e32 v118, v172, v118
	v_mul_f32_e32 v119, v172, v119
	v_mul_f32_e32 v112, v172, v112
	v_mfma_f32_16x16x32_bf16 v[8:11], v[160:163], v[216:219], v[8:11]
	v_mul_f32_e32 v113, v172, v113
	v_mul_f32_e32 v114, v172, v114
	v_mul_f32_e32 v115, v172, v115
	v_cvt_pk_bf16_f32 v116, v116, v117
	v_cvt_pk_bf16_f32 v117, v118, v119
	v_mfma_f32_16x16x32_bf16 v[60:63], v[156:159], v[196:199], v[60:63]
	v_cvt_pk_bf16_f32 v118, v112, v113
	v_cvt_pk_bf16_f32 v119, v114, v115
	global_store_dwordx4 v[232:233], v[116:119], off offset:256
	v_lshl_add_u64 v[232:233], v[232:233], 0, s[98:99]
	v_mul_f32_e32 v108, v173, v108
	v_mfma_f32_16x16x32_bf16 v[56:59], v[164:167], v[196:199], v[56:59]
	v_mul_f32_e32 v109, v173, v109
	v_mul_f32_e32 v110, v173, v110
	v_mul_f32_e32 v111, v173, v111
	v_mul_f32_e32 v104, v173, v104
	v_mul_f32_e32 v105, v173, v105
	v_mfma_f32_16x16x32_bf16 v[44:47], v[156:159], v[204:207], v[44:47]
	v_mul_f32_e32 v106, v173, v106
	v_mul_f32_e32 v107, v173, v107
	v_cvt_pk_bf16_f32 v108, v108, v109
	v_cvt_pk_bf16_f32 v109, v110, v111
	v_cvt_pk_bf16_f32 v110, v104, v105
	v_mfma_f32_16x16x32_bf16 v[40:43], v[164:167], v[204:207], v[40:43]
	v_cvt_pk_bf16_f32 v111, v106, v107
	global_store_dwordx4 v[232:233], v[108:111], off
	v_mul_f32_e32 v100, v173, v100
	v_mul_f32_e32 v101, v173, v101
	v_mul_f32_e32 v102, v173, v102
	v_mfma_f32_16x16x32_bf16 v[28:31], v[156:159], v[212:215], v[28:31]
; #define PG8_MMA(ai, bj, At, Bt) do { __builtin_amdgcn_s_setprio(1); _Pragma("unroll") for (int k = 0; k < 2; ++k) _Pragma("unroll") for (int m = 0; m < 4; ++m) _Pragma("unroll") for (int n = 0; n < 2; ++n) \
;         acc[ai][bj][m][n] = __builtin_amdgcn_mfma_f32_16x16x32_bf16(Bt[n][k], At[m][k], acc[ai][bj][m][n], 0, 0, 0); __builtin_amdgcn_s_setprio(0); } while (0)
; #define PG8_WAIT_V(n) asm volatile("s_waitcnt vmcnt(" #n ")" ::: "memory")
; #define PG8_WAIT_L(n) asm volatile("s_waitcnt lgkmcnt(" #n ")" ::: "memory")
; #define PG8_BAR __builtin_amdgcn_s_barrier()
; #define PG8_SCHED __builtin_amdgcn_sched_barrier(0)
; template <class Epi, bool ALIGN_EPI>
; __device__ __forceinline__ void gemm_phase(LAS unsigned char* lds, const Gemm g, const StaticOrder& S, const Epi& E, const int tid) {
;     ...
;             PG8_WAIT_V(8); PG8_WAIT_L(0); PG8_BAR; PG8_MMA(1, 0, At, B0); PG8_MMA(1, 1, At, B1); PG8_BAR; PG8_SCHED;
;     ...
;         if (!has_next) break;
;     ...
;         cur = nxt; cA = nA; cB = nB; ++ui;
	v_mul_f32_e32 v103, v173, v103
	v_mul_f32_e32 v96, v173, v96
	v_mul_f32_e32 v97, v173, v97
	v_mul_f32_e32 v98, v173, v98
	v_mul_f32_e32 v99, v173, v99
	v_mfma_f32_16x16x32_bf16 v[24:27], v[164:167], v[212:215], v[24:27]
	v_cvt_pk_bf16_f32 v100, v100, v101
	v_cvt_pk_bf16_f32 v101, v102, v103
	v_cvt_pk_bf16_f32 v102, v96, v97
	v_cvt_pk_bf16_f32 v103, v98, v99
	global_store_dwordx4 v[232:233], v[100:103], off offset:256
	v_mfma_f32_16x16x32_bf16 v[12:15], v[156:159], v[240:243], v[12:15]
	v_lshl_add_u64 v[232:233], v[232:233], 0, s[98:99]
	v_mul_f32_e32 v92, v236, v92
	v_mul_f32_e32 v93, v236, v93
	v_mul_f32_e32 v94, v236, v94
	v_mul_f32_e32 v95, v236, v95
	v_mfma_f32_16x16x32_bf16 v[8:11], v[164:167], v[240:243], v[8:11]
	v_mul_f32_e32 v88, v236, v88
	v_mul_f32_e32 v89, v236, v89
	v_mul_f32_e32 v90, v236, v90
	v_mul_f32_e32 v91, v236, v91
	v_cvt_pk_bf16_f32 v92, v92, v93
	s_setprio 0
	s_setprio 1
	v_mfma_f32_16x16x32_bf16 v[52:55], v[176:179], v[192:195], v[52:55]
	v_cvt_pk_bf16_f32 v93, v94, v95
	v_cvt_pk_bf16_f32 v94, v88, v89
	v_cvt_pk_bf16_f32 v95, v90, v91
	global_store_dwordx4 v[232:233], v[92:95], off
	v_mul_f32_e32 v84, v236, v84
	v_mfma_f32_16x16x32_bf16 v[48:51], v[184:187], v[192:195], v[48:51]
	v_mul_f32_e32 v85, v236, v85
	v_mul_f32_e32 v86, v236, v86
	v_mul_f32_e32 v87, v236, v87
	v_mul_f32_e32 v80, v236, v80
	v_mul_f32_e32 v81, v236, v81
	v_mfma_f32_16x16x32_bf16 v[36:39], v[176:179], v[200:203], v[36:39]
	v_mul_f32_e32 v82, v236, v82
	v_mul_f32_e32 v83, v236, v83
	v_cvt_pk_bf16_f32 v84, v84, v85
	v_cvt_pk_bf16_f32 v85, v86, v87
	v_cvt_pk_bf16_f32 v86, v80, v81
	v_mfma_f32_16x16x32_bf16 v[32:35], v[184:187], v[200:203], v[32:35]
	v_cvt_pk_bf16_f32 v87, v82, v83
	global_store_dwordx4 v[232:233], v[84:87], off offset:256
	v_lshl_add_u64 v[232:233], v[232:233], 0, s[98:99]
	v_mul_f32_e32 v76, v237, v76
	v_mul_f32_e32 v77, v237, v77
	v_mfma_f32_16x16x32_bf16 v[20:23], v[176:179], v[208:211], v[20:23]
	v_mul_f32_e32 v78, v237, v78
	v_mul_f32_e32 v79, v237, v79
	v_mul_f32_e32 v72, v237, v72
	v_mul_f32_e32 v73, v237, v73
	v_mul_f32_e32 v74, v237, v74
	v_mfma_f32_16x16x32_bf16 v[16:19], v[184:187], v[208:211], v[16:19]
	v_mul_f32_e32 v75, v237, v75
	v_cvt_pk_bf16_f32 v76, v76, v77
	v_cvt_pk_bf16_f32 v77, v78, v79
	v_cvt_pk_bf16_f32 v78, v72, v73
	v_cvt_pk_bf16_f32 v79, v74, v75
	v_mfma_f32_16x16x32_bf16 v[4:7], v[176:179], v[216:219], v[4:7]
	global_store_dwordx4 v[232:233], v[76:79], off
	v_mul_f32_e32 v68, v237, v68
	v_mul_f32_e32 v69, v237, v69
	v_mul_f32_e32 v70, v237, v70
	v_mul_f32_e32 v71, v237, v71
	v_mfma_f32_16x16x32_bf16 v[0:3], v[184:187], v[216:219], v[0:3]
	v_mul_f32_e32 v64, v237, v64
	v_mul_f32_e32 v65, v237, v65
	v_mul_f32_e32 v66, v237, v66
	v_mul_f32_e32 v67, v237, v67
	v_cvt_pk_bf16_f32 v68, v68, v69
	v_mfma_f32_16x16x32_bf16 v[52:55], v[180:183], v[196:199], v[52:55]
	v_cvt_pk_bf16_f32 v69, v70, v71
	v_cvt_pk_bf16_f32 v70, v64, v65
	v_cvt_pk_bf16_f32 v71, v66, v67
	global_store_dwordx4 v[232:233], v[68:71], off offset:256
	v_lshl_add_u64 v[232:233], v[232:233], 0, s[98:99]
	v_mfma_f32_16x16x32_bf16 v[48:51], v[188:191], v[196:199], v[48:51]
	v_lshl_add_u64 v[232:233], v[232:233], 0, s[98:99]
	v_lshl_add_u64 v[232:233], v[232:233], 0, s[98:99]
	v_lshl_add_u64 v[232:233], v[232:233], 0, s[98:99]
	v_lshl_add_u64 v[232:233], v[232:233], 0, s[98:99]
	v_mfma_f32_16x16x32_bf16 v[36:39], v[180:183], v[204:207], v[36:39]
	v_mfma_f32_16x16x32_bf16 v[32:35], v[188:191], v[204:207], v[32:35]
	v_mfma_f32_16x16x32_bf16 v[20:23], v[180:183], v[212:215], v[20:23]
	v_mfma_f32_16x16x32_bf16 v[16:19], v[188:191], v[212:215], v[16:19]
	v_mfma_f32_16x16x32_bf16 v[4:7], v[180:183], v[240:243], v[4:7]
	v_mfma_f32_16x16x32_bf16 v[0:3], v[188:191], v[240:243], v[0:3]
	s_setprio 0
	s_barrier
	v_lshl_add_u64 v[142:143], v[142:143], 0, s[80:81]
	v_lshl_add_u64 v[144:145], v[144:145], 0, s[80:81]
	s_and_b64 vcc, exec, s[8:9]
	s_cbranch_vccnz .Lq5_notdefer
	s_cmp_lg_u32 s59, s61
	s_cbranch_scc1 .Lq5_notdefer
	s_mov_b32 s101, 1
	s_mov_b32 s60, s58
	s_mov_b32 s61, s59
	v_mov_b64_e32 v[144:145], v[140:141]
	v_mov_b64_e32 v[142:143], v[138:139]
	s_branch .LBB0_346
